# S5 plus softmax-finish cvt/permlane woven into QK MFMAs and DMA nops dropped (fine-grained LDS waits kept)
# speedup vs baseline: 1.0045x; 1.0045x over previous
; __device__ __forceinline__ void finishSM(f32x16& p0, f32x16& p1, float alpha, float& l_reg, bf16x8& pa0, bf16x8& pa1, bf16x8& pa2, bf16x8& pa3) {
;   for (int r = 0; r < 16; ++r) p1[r] = __builtin_amdgcn_exp2f(p1[r]);
;   float ps = 0; for (int r = 0; r < 16; ++r) ps += p0[r]; for (int r = 0; r < 16; ++r) ps += p1[r];
;   { auto rr = __builtin_amdgcn_permlane32_swap(__float_as_uint(ps), __float_as_uint(ps), false, false);
;     ps = __uint_as_float(rr[0]) + __uint_as_float(rr[1]); }
;   l_reg = l_reg * alpha + ps;
;     ...
;   PK4(p0, 0, pa0); PK4(p0, 8, pa1); PK4(p1, 0, pa2); PK4(p1, 8, pa3);
;     ...
; }
; __device__ __forceinline__ void kload(bf16x8 (&kf)[8], const char* Ks, int r32, int hi, int sb) {
; #pragma unroll
;   for (int d0 = 0; d0 < 4; ++d0) { const int cb = sb + (d0 * 16 + hi * 8) * 2;
;     kf[2 * d0] = *reinterpret_cast<const bf16x8*>(Ks + KSWZ(r32, cb)); kf[2 * d0 + 1] = *reinterpret_cast<const bf16x8*>(Ks + KSWZ(32 + r32, cb)); }
; }
; __device__ __forceinline__ void kmma(f32x16& p0, f32x16& p1, const bf16x8 (&kf)[8], const bf16x8* qr) {
;   asm volatile("s_waitcnt lgkmcnt(0)" ::: "memory"); SBAR();
;   p0 = f32x16{}; p1 = f32x16{};
; #pragma unroll
;   for (int d0 = 0; d0 < 4; ++d0) { p0 = __builtin_amdgcn_mfma_f32_32x32x16_bf16(kf[2 * d0], qr[d0], p0, 0, 0, 0); p1 = __builtin_amdgcn_mfma_f32_32x32x16_bf16(kf[2 * d0 + 1], qr[d0], p1, 0, 0, 0); }
; }
; __device__ __forceinline__ void qkt(f32x16& p0, f32x16& p1, const char* Ks, const bf16x8* qr, int r32, int hi, int sb) {
;   bf16x8 kf[8]; kload(kf, Ks, r32, hi, sb); SBAR(); kmma(p0, p1, kf, qr);
; }
; __device__ __forceinline__ int v_st(int k, int c) { const int kk = (k & ~0xC) | ((k & 4) << 1) | ((k & 8) >> 1); return ((kk >> 3) * 4 + (c >> 5)) * 512 + ((kk & 7) * 32 + (c & 31)) * 2; }
; __device__ __forceinline__ int v_rd_base(int lane) { return ((lane & 3) << 3) | (((lane >> 2) & 3) << 6) | (((lane >> 4) & 1) << 5) | (((lane >> 5) & 1) << 8); }
; template <int OFF> __device__ __forceinline__ s16x4 tr_read(int vb) {
;   s16x4 r; asm volatile("ds_read_b64_tr_b16 %0, %1 offset:%2" : "=&v"(r) : "v"(vb), "i"(OFF) : "memory"); return r;
; }
; template <int D0> __device__ __forceinline__ void v_frag_read(VFrag& f, int vb) {
;   f.l0 = tr_read<v_rd_off(D0, 0, 0)>(vb); f.h0 = tr_read<v_rd_off(D0, 0, 1)>(vb); f.l1 = tr_read<v_rd_off(D0, 1, 0)>(vb); f.h1 = tr_read<v_rd_off(D0, 1, 1)>(vb);
.LBB0_770:
	s_and_b32 s0, s12, 0xff
	s_mulk_i32 s0, 0xab
	s_lshr_b32 s0, s0, 9
	s_mul_i32 s0, s0, 3
	s_sub_i32 s0, s12, s0
	s_and_b32 s0, s0, 0xff
	s_lshl_b32 s0, s0, 14
	s_add_i32 s0, s0, 0
	v_add_u32_e32 v86, s0, v169
	v_add_u32_e32 v90, s0, v170
	ds_read_b128 v[82:85], v86
	ds_read_b128 v[86:89], v86 offset:8192
	ds_read_b128 v[130:133], v90
	ds_read_b128 v[134:137], v90 offset:8192
	v_add_u32_e32 v90, s0, v171
	ds_read_b128 v[206:209], v90
	ds_read_b128 v[210:213], v90 offset:8192
	v_add_u32_e32 v90, s0, v172
	ds_read_b128 v[214:217], v90
	ds_read_b128 v[218:221], v90 offset:8192
	s_and_b32 s13, s36, 0xc000
	v_add_u32_e32 v244, s13, v164
	ds_read_b64_tr_b16 v[228:229], v244 offset:0
	ds_read_b64_tr_b16 v[230:231], v244 offset:0x800
	ds_read_b64_tr_b16 v[232:233], v244 offset:0x1000
	ds_read_b64_tr_b16 v[234:235], v244 offset:0x1800
	ds_read_b64_tr_b16 v[236:237], v244 offset:0x2000
	ds_read_b64_tr_b16 v[238:239], v244 offset:0x2800
	ds_read_b64_tr_b16 v[240:241], v244 offset:0x3000
	ds_read_b64_tr_b16 v[242:243], v244 offset:0x3800
	v_exp_f32_e32 v148, v66
	v_add_f32_e32 v66, 0, v175
	v_add_f32_e32 v66, v177, v66
	v_add_f32_e32 v66, v192, v66
	v_add_f32_e32 v66, v195, v66
	v_add_f32_e32 v66, v196, v66
	v_add_f32_e32 v66, v199, v66
	v_add_f32_e32 v66, v200, v66
	v_add_f32_e32 v66, v203, v66
	v_add_f32_e32 v66, v176, v66
	v_add_f32_e32 v66, v193, v66
	v_add_f32_e32 v66, v194, v66
	v_add_f32_e32 v66, v197, v66
	v_add_f32_e32 v66, v198, v66
	v_exp_f32_e32 v149, v67
	v_add_f32_e32 v66, v201, v66
	s_waitcnt lgkmcnt(15)
	v_mfma_f32_32x32x16_bf16 v[98:113], v[82:85], v[126:129], 0
	v_exp_f32_e32 v150, v68
	s_add_i32 s37, s12, 2
	v_add_f32_e32 v66, v202, v66
	s_cmpk_lt_u32 s12, 0x7e
	v_exp_f32_e32 v151, v69
	s_cselect_b64 s[0:1], -1, 0
	v_add_f32_e32 v66, v204, v66
	s_and_b64 s[10:11], s[0:1], exec
	v_exp_f32_e32 v186, v70
	s_cselect_b32 s10, 0, 0xffffff80
	v_add_f32_e32 v66, v148, v66
	v_exp_f32_e32 v187, v71
	s_waitcnt lgkmcnt(14)
	v_mfma_f32_32x32x16_bf16 v[82:97], v[86:89], v[126:129], 0
	v_add_f32_e32 v66, v149, v66
	s_add_i32 s58, s37, s10
	v_exp_f32_e32 v188, v72
	s_and_b64 s[0:1], s[0:1], exec
	v_add_f32_e32 v66, v150, v66
	s_cselect_b32 s1, s9, s30
	v_exp_f32_e32 v189, v73
	s_cselect_b32 s0, s8, s26
	v_add_f32_e32 v66, v151, v66
	s_lshl_b64 s[10:11], s[58:59], 17
	v_exp_f32_e32 v205, v74
	v_add_f32_e32 v66, v186, v66
	s_waitcnt lgkmcnt(13)
	v_mfma_f32_32x32x16_bf16 v[98:113], v[130:133], v[122:125], v[98:113]
	v_exp_f32_e32 v222, v75
	s_lshl_b64 s[0:1], s[0:1], 11
	v_add_f32_e32 v66, v187, v66
	s_add_u32 s10, s10, s0
	v_exp_f32_e32 v223, v76
	s_addc_u32 s11, s11, s1
	v_add_f32_e32 v66, v188, v66
	s_add_u32 s0, s20, s10
	v_exp_f32_e32 v224, v77
	s_addc_u32 s1, s21, s11
	v_add_f32_e32 v66, v189, v66
	v_exp_f32_e32 v225, v78
	s_waitcnt lgkmcnt(12)
	v_mfma_f32_32x32x16_bf16 v[82:97], v[134:137], v[122:125], v[82:97]
	v_add_f32_e32 v66, v205, v66
	s_add_u32 s10, s22, s10
	v_exp_f32_e32 v226, v79
	s_addc_u32 s11, s23, s11
	v_add_f32_e32 v66, v222, v66
	s_and_b32 s13, s37, 0xff
	v_exp_f32_e32 v227, v80
	s_mulk_i32 s13, 0xab
	v_add_f32_e32 v66, v223, v66
	s_lshr_b32 s13, s13, 9
	v_exp_f32_e32 v81, v81
	v_add_f32_e32 v66, v224, v66
	v_add_f32_e32 v66, v225, v66
	s_waitcnt lgkmcnt(11)
	v_mfma_f32_32x32x16_bf16 v[98:113], v[206:209], v[118:121], v[98:113]
	v_add_f32_e32 v66, v226, v66
	s_mul_i32 s13, s13, 3
	v_add_f32_e32 v66, v227, v66
	s_sub_i32 s13, s37, s13
	v_add_f32_e32 v130, v81, v66
	s_and_b32 s13, s13, 0xff
	v_mov_b32_e32 v131, v130
	s_lshl_b32 s13, s13, 14
	v_cvt_pk_bf16_f32 v66, v175, v177
	s_add_i32 s42, s36, 0xffffc000
	v_cvt_pk_bf16_f32 v67, v192, v195
	v_cvt_pk_bf16_f32 v68, v196, v199
	s_waitcnt lgkmcnt(10)
	v_mfma_f32_32x32x16_bf16 v[82:97], v[210:213], v[118:121], v[82:97]
	v_permlane32_swap_b32_e32 v130, v131
	s_and_b32 s42, s42, 0xc000
	v_cvt_pk_bf16_f32 v69, v200, v203
	s_add_i32 s13, s13, s27
	v_permlane32_swap_b32_e32 v66, v68
	s_add_i32 s42, s42, s31
	v_cvt_pk_bf16_f32 v70, v176, v193
	v_lshl_add_u64 v[246:247], s[0:1], 0, v[146:147]
	v_cvt_pk_bf16_f32 v71, v194, v197
	s_mov_b32 m0, s13
	v_cvt_pk_bf16_f32 v72, v198, v201
	v_cvt_pk_bf16_f32 v73, v202, v204
	s_waitcnt lgkmcnt(9)
	v_mfma_f32_32x32x16_bf16 v[98:113], v[214:217], v[114:117], v[98:113]
	v_cvt_pk_bf16_f32 v74, v148, v149
	global_load_lds_dwordx4 v[246:247], off
	v_cvt_pk_bf16_f32 v75, v150, v151
	v_lshl_add_u64 v[246:247], s[10:11], 0, v[142:143]
	v_cvt_pk_bf16_f32 v76, v186, v187
	s_mov_b32 m0, s42
	v_cvt_pk_bf16_f32 v77, v188, v189
	global_load_lds_dwordx4 v[246:247], off
	v_cvt_pk_bf16_f32 v78, v205, v222
	v_lshl_add_u64 v[246:247], s[0:1], 0, v[144:145]
	v_cvt_pk_bf16_f32 v79, v223, v224
	v_cvt_pk_bf16_f32 v80, v225, v226
	s_waitcnt lgkmcnt(8)
	v_mfma_f32_32x32x16_bf16 v[82:97], v[218:221], v[114:117], v[82:97]
	v_cvt_pk_bf16_f32 v81, v227, v81
	s_add_i32 m0, s13, 0x2000
	v_permlane32_swap_b32_e32 v67, v69
	global_load_lds_dwordx4 v[246:247], off
	v_permlane32_swap_b32_e32 v70, v72
	v_lshl_add_u64 v[246:247], s[10:11], 0, v[154:155]
	v_permlane32_swap_b32_e32 v71, v73
	s_add_i32 m0, s42, 0x2000
	v_permlane32_swap_b32_e32 v74, v76
	global_load_lds_dwordx4 v[246:247], off
	v_permlane32_swap_b32_e32 v75, v77
	v_permlane32_swap_b32_e32 v78, v80
	v_permlane32_swap_b32_e32 v79, v81
	ds_read_b64_tr_b16 v[204:205], v244 offset:0x200
	ds_read_b64_tr_b16 v[206:207], v244 offset:0xa00
	ds_read_b64_tr_b16 v[208:209], v244 offset:0x1200
	ds_read_b64_tr_b16 v[210:211], v244 offset:0x1a00
	ds_read_b64_tr_b16 v[212:213], v244 offset:0x2200
	ds_read_b64_tr_b16 v[214:215], v244 offset:0x2a00
	ds_read_b64_tr_b16 v[216:217], v244 offset:0x3200
	ds_read_b64_tr_b16 v[218:219], v244 offset:0x3a00
	s_waitcnt lgkmcnt(14)
; __device__ __forceinline__ void partialSM(f32x16& p0, f32x16& p1, float& m_reg, float& mn, float& alpha) {
;   constexpr float C = SCALE * 1.4426950408889634f;
;   float pmax = p0[0]; for (int r = 1; r < 16; ++r) pmax = fmaxf(pmax, p0[r]); for (int r = 0; r < 16; ++r) pmax = fmaxf(pmax, p1[r]);
;   { auto rr = __builtin_amdgcn_permlane32_swap(__float_as_uint(pmax), __float_as_uint(pmax), false, false);
;     pmax = fmaxf(__uint_as_float(rr[0]), __uint_as_float(rr[1])); }
;   if (__builtin_expect(__all(pmax - m_reg <= THR / SCALE), 1)) { mn = m_reg; alpha = 1.f; }
;   else { mn = fmaxf(m_reg, pmax); alpha = __builtin_amdgcn_exp2f((m_reg - mn) * C); m_reg = mn; }
;   float mnC = -mn * C;
;   for (int r = 0; r < 16; ++r) p0[r] = fmaf(p0[r], C, mnC); for (int r = 0; r < 16; ++r) p1[r] = fmaf(p1[r], C, mnC);
;   for (int r = 0; r < 16; ++r) p0[r] = __builtin_amdgcn_exp2f(p0[r]);
; }
; template <int D0> __device__ __forceinline__ void v_frag_read(VFrag& f, int vb) {
;   f.l0 = tr_read<v_rd_off(D0, 0, 0)>(vb); f.h0 = tr_read<v_rd_off(D0, 0, 1)>(vb); f.l1 = tr_read<v_rd_off(D0, 1, 0)>(vb); f.h1 = tr_read<v_rd_off(D0, 1, 1)>(vb);
;   f.l2 = tr_read<v_rd_off(D0, 2, 0)>(vb); f.h2 = tr_read<v_rd_off(D0, 2, 1)>(vb); f.l3 = tr_read<v_rd_off(D0, 3, 0)>(vb); f.h3 = tr_read<v_rd_off(D0, 3, 1)>(vb);
; }
; __device__ __forceinline__ void pv_mma(f32x16& od, const VFrag& f, bf16x8 pa0, bf16x8 pa1, bf16x8 pa2, bf16x8 pa3) {
;     ...
;   od = __builtin_amdgcn_mfma_f32_32x32x16_bf16(pa0, PK(f.l0, f.h0), od, 0, 0, 0);
;   od = __builtin_amdgcn_mfma_f32_32x32x16_bf16(pa1, PK(f.l1, f.h1), od, 0, 0, 0);
;   od = __builtin_amdgcn_mfma_f32_32x32x16_bf16(pa2, PK(f.l2, f.h2), od, 0, 0, 0);
;   od = __builtin_amdgcn_mfma_f32_32x32x16_bf16(pa3, PK(f.l3, f.h3), od, 0, 0, 0);
;     ...
; }
; __device__ __forceinline__ void pv_d0(f32x16* o, int vb, bf16x8 pa0, bf16x8 pa1, bf16x8 pa2, bf16x8 pa3) {
;   VFrag fa, fb;
;   v_frag_read<0>(fa, vb);
;   asm volatile("s_waitcnt lgkmcnt(0)" ::: "memory"); SBAR();
;   v_frag_read<1>(fb, vb); SBAR();
;   pv_mma(o[0], fa, pa0, pa1, pa2, pa3); SBAR();
;   asm volatile("s_waitcnt lgkmcnt(0)" ::: "memory"); SBAR();
;   v_frag_read<2>(fa, vb); SBAR();
;   pv_mma(o[1], fb, pa0, pa1, pa2, pa3); SBAR();
;   asm volatile("s_waitcnt lgkmcnt(0)" ::: "memory"); SBAR();
;   v_frag_read<3>(fb, vb); SBAR();
;   pv_mma(o[2], fa, pa0, pa1, pa2, pa3); SBAR();
	v_mfma_f32_32x32x16_bf16 v[18:33], v[66:69], v[228:231], v[18:33]
	v_max_f32_e32 v245, v99, v99
	v_max_f32_e32 v246, v98, v98
	v_max_f32_e32 v245, v246, v245
	v_max3_f32 v245, v245, v100, v101
	v_max3_f32 v245, v245, v102, v103
	v_max3_f32 v245, v245, v104, v105
	v_max3_f32 v245, v245, v106, v107
	v_max3_f32 v245, v245, v108, v109
	s_waitcnt lgkmcnt(12)
	v_mfma_f32_32x32x16_bf16 v[18:33], v[70:73], v[232:235], v[18:33]
	v_max3_f32 v245, v245, v110, v111
	v_max3_f32 v245, v245, v112, v113
	v_max3_f32 v245, v245, v82, v83
	v_max3_f32 v245, v245, v84, v85
	v_max3_f32 v245, v245, v86, v87
	v_max3_f32 v245, v245, v88, v89
	v_max3_f32 v245, v245, v90, v91
	v_max3_f32 v245, v245, v92, v93
	s_waitcnt lgkmcnt(10)
	v_mfma_f32_32x32x16_bf16 v[18:33], v[74:77], v[236:239], v[18:33]
	v_max3_f32 v245, v245, v94, v95
	v_max3_f32 v245, v245, v96, v97
	v_mov_b32_e32 v246, v245
	s_nop 1
	v_permlane32_swap_b32_e32 v245, v246
	v_max_f32_e32 v246, v246, v246
	v_max_f32_e32 v245, v245, v245
	v_max_f32_e32 v245, v245, v246
	v_sub_f32_e32 v246, v245, v174
	s_waitcnt lgkmcnt(8)
	v_mfma_f32_32x32x16_bf16 v[18:33], v[78:81], v[240:243], v[18:33]
	v_cmp_ge_f32_e32 vcc, s63, v246
	v_max_f32_e32 v246, v174, v174
	v_max_f32_e32 v245, v246, v245
	v_sub_f32_e32 v246, v174, v245
	v_mul_f32_e32 v246, 0x3e38aa3b, v246
	v_exp_f32_e32 v246, v246
	s_cmp_eq_u64 vcc, exec
	s_cselect_b64 s[0:1], -1, 0
	v_cndmask_b32_e64 v132, v246, 1.0, s[0:1]
	ds_read_b64_tr_b16 v[228:229], v244 offset:0x400
	ds_read_b64_tr_b16 v[230:231], v244 offset:0xc00
	ds_read_b64_tr_b16 v[232:233], v244 offset:0x1400
	ds_read_b64_tr_b16 v[234:235], v244 offset:0x1c00
	ds_read_b64_tr_b16 v[236:237], v244 offset:0x2400
	ds_read_b64_tr_b16 v[238:239], v244 offset:0x2c00
	ds_read_b64_tr_b16 v[240:241], v244 offset:0x3400
	ds_read_b64_tr_b16 v[242:243], v244 offset:0x3c00
	v_cndmask_b32_e64 v133, v245, v174, s[0:1]
	v_mul_f32_e32 v148, 0xbe38aa3b, v133
	s_waitcnt lgkmcnt(14)
	v_mfma_f32_32x32x16_bf16 v[50:65], v[66:69], v[204:207], v[50:65]
	v_fmamk_f32 v98, v98, 0x3e38aa3b, v148
	v_fmamk_f32 v99, v99, 0x3e38aa3b, v148
	v_fmamk_f32 v100, v100, 0x3e38aa3b, v148
	v_fmamk_f32 v101, v101, 0x3e38aa3b, v148
	s_waitcnt lgkmcnt(12)
	v_mfma_f32_32x32x16_bf16 v[50:65], v[70:73], v[208:211], v[50:65]
	v_fmamk_f32 v102, v102, 0x3e38aa3b, v148
	v_fmamk_f32 v103, v103, 0x3e38aa3b, v148
	v_fmamk_f32 v104, v104, 0x3e38aa3b, v148
	v_fmamk_f32 v105, v105, 0x3e38aa3b, v148
	s_waitcnt lgkmcnt(10)
	v_mfma_f32_32x32x16_bf16 v[50:65], v[74:77], v[212:215], v[50:65]
	v_fmamk_f32 v106, v106, 0x3e38aa3b, v148
	v_fmamk_f32 v107, v107, 0x3e38aa3b, v148
	v_fmamk_f32 v108, v108, 0x3e38aa3b, v148
	v_fmamk_f32 v109, v109, 0x3e38aa3b, v148
	s_waitcnt lgkmcnt(8)
	v_mfma_f32_32x32x16_bf16 v[50:65], v[78:81], v[216:219], v[50:65]
	v_fmamk_f32 v110, v110, 0x3e38aa3b, v148
	v_fmamk_f32 v111, v111, 0x3e38aa3b, v148
	v_fmamk_f32 v112, v112, 0x3e38aa3b, v148
	v_fmamk_f32 v113, v113, 0x3e38aa3b, v148
	ds_read_b64_tr_b16 v[204:205], v244 offset:0x600
	ds_read_b64_tr_b16 v[206:207], v244 offset:0xe00
	ds_read_b64_tr_b16 v[208:209], v244 offset:0x1600
	ds_read_b64_tr_b16 v[210:211], v244 offset:0x1e00
	ds_read_b64_tr_b16 v[212:213], v244 offset:0x2600
	ds_read_b64_tr_b16 v[214:215], v244 offset:0x2e00
	ds_read_b64_tr_b16 v[216:217], v244 offset:0x3600
	ds_read_b64_tr_b16 v[218:219], v244 offset:0x3e00
	s_waitcnt lgkmcnt(14)
	v_mfma_f32_32x32x16_bf16 v[34:49], v[66:69], v[228:231], v[34:49]
	v_fmamk_f32 v82, v82, 0x3e38aa3b, v148
	v_fmamk_f32 v83, v83, 0x3e38aa3b, v148
	v_fmamk_f32 v84, v84, 0x3e38aa3b, v148
	v_fmamk_f32 v85, v85, 0x3e38aa3b, v148
	s_waitcnt lgkmcnt(12)
	v_mfma_f32_32x32x16_bf16 v[34:49], v[70:73], v[232:235], v[34:49]
	v_fmamk_f32 v86, v86, 0x3e38aa3b, v148
	v_fmamk_f32 v87, v87, 0x3e38aa3b, v148
	s_add_i32 s13, s36, 0xffff4000
	v_fmamk_f32 v149, v88, 0x3e38aa3b, v148
	s_waitcnt lgkmcnt(10)
	v_mfma_f32_32x32x16_bf16 v[34:49], v[74:77], v[236:239], v[34:49]
	v_fmamk_f32 v150, v89, 0x3e38aa3b, v148
	v_fmamk_f32 v151, v90, 0x3e38aa3b, v148
	v_fmamk_f32 v186, v91, 0x3e38aa3b, v148
	v_fmamk_f32 v187, v92, 0x3e38aa3b, v148
	s_waitcnt lgkmcnt(8)
	v_mfma_f32_32x32x16_bf16 v[34:49], v[78:81], v[240:243], v[34:49]
	v_fmamk_f32 v188, v93, 0x3e38aa3b, v148
	v_fmamk_f32 v189, v94, 0x3e38aa3b, v148
	v_exp_f32_e32 v192, v98
	v_exp_f32_e32 v193, v99
	v_exp_f32_e32 v194, v100
	v_exp_f32_e32 v195, v101
	s_waitcnt lgkmcnt(6)
	v_mfma_f32_32x32x16_bf16 v[2:17], v[66:69], v[204:207], v[2:17]
	v_exp_f32_e32 v196, v102
	v_exp_f32_e32 v197, v103
	v_exp_f32_e32 v198, v104
	v_exp_f32_e32 v199, v105
	s_waitcnt lgkmcnt(4)
	v_mfma_f32_32x32x16_bf16 v[2:17], v[70:73], v[208:211], v[2:17]
	v_exp_f32_e32 v200, v106
	v_exp_f32_e32 v201, v107
	v_exp_f32_e32 v202, v108
	v_exp_f32_e32 v203, v109
	v_exp_f32_e32 v204, v110
	v_exp_f32_e32 v205, v111
	s_waitcnt lgkmcnt(2)
	v_mfma_f32_32x32x16_bf16 v[2:17], v[74:77], v[212:215], v[2:17]
	v_exp_f32_e32 v206, v112
	v_exp_f32_e32 v207, v113
	v_fmamk_f32 v208, v95, 0x3e38aa3b, v148
	v_fmamk_f32 v209, v96, 0x3e38aa3b, v148
	v_fmac_f32_e32 v148, 0x3e38aa3b, v97
	s_waitcnt lgkmcnt(0)
	v_mfma_f32_32x32x16_bf16 v[2:17], v[78:81], v[216:219], v[2:17]
	v_cmp_gt_f32_e32 vcc, 1.0, v132
	s_cbranch_vccz .LBB0_774
	s_and_saveexec_b64 s[10:11], s[40:41]
	ds_write_b32 v162, v132 offset:128
	s_or_b64 exec, exec, s[10:11]
	s_waitcnt lgkmcnt(0)
	v_add_u32_e32 v67, s18, v140
	ds_read_b128 v[68:71], v67 offset:224
	ds_read_b128 v[72:75], v67 offset:192
	ds_read_b128 v[76:79], v67 offset:160
	ds_read_b128 v[134:137], v67 offset:128
	s_waitcnt lgkmcnt(0)
	v_pk_mul_f32 v[30:31], v[30:31], v[68:69]
	v_pk_mul_f32 v[26:27], v[26:27], v[72:73]
	v_pk_mul_f32 v[22:23], v[22:23], v[76:77]
	v_pk_mul_f32 v[32:33], v[32:33], v[70:71]
	v_pk_mul_f32 v[28:29], v[28:29], v[74:75]
	v_pk_mul_f32 v[24:25], v[24:25], v[78:79]
	v_pk_mul_f32 v[20:21], v[20:21], v[136:137]
	v_pk_mul_f32 v[18:19], v[18:19], v[134:135]
	v_pk_mul_f32 v[62:63], v[62:63], v[68:69]
	v_pk_mul_f32 v[58:59], v[58:59], v[72:73]
	v_pk_mul_f32 v[54:55], v[54:55], v[76:77]
	v_pk_mul_f32 v[64:65], v[64:65], v[70:71]
	v_pk_mul_f32 v[60:61], v[60:61], v[74:75]
	v_pk_mul_f32 v[56:57], v[56:57], v[78:79]
	v_pk_mul_f32 v[52:53], v[52:53], v[136:137]
	v_pk_mul_f32 v[50:51], v[50:51], v[134:135]
	v_pk_mul_f32 v[46:47], v[46:47], v[68:69]
	v_pk_mul_f32 v[42:43], v[42:43], v[72:73]
	v_pk_mul_f32 v[38:39], v[38:39], v[76:77]
	v_pk_mul_f32 v[48:49], v[48:49], v[70:71]
	v_pk_mul_f32 v[44:45], v[44:45], v[74:75]
	v_pk_mul_f32 v[40:41], v[40:41], v[78:79]
	v_pk_mul_f32 v[36:37], v[36:37], v[136:137]
	v_pk_mul_f32 v[34:35], v[34:35], v[134:135]
	v_pk_mul_f32 v[14:15], v[14:15], v[68:69]
	v_pk_mul_f32 v[10:11], v[10:11], v[72:73]
	v_pk_mul_f32 v[6:7], v[6:7], v[76:77]
	v_pk_mul_f32 v[16:17], v[16:17], v[70:71]
	v_pk_mul_f32 v[12:13], v[12:13], v[74:75]
	v_pk_mul_f32 v[8:9], v[8:9], v[78:79]
	v_pk_mul_f32 v[4:5], v[4:5], v[136:137]
	v_pk_mul_f32 v[2:3], v[2:3], v[134:135]
; #define SBAR() __builtin_amdgcn_sched_barrier(0)
; __device__ __forceinline__ void finishSM(f32x16& p0, f32x16& p1, float alpha, float& l_reg, bf16x8& pa0, bf16x8& pa1, bf16x8& pa2, bf16x8& pa3) {
;   for (int r = 0; r < 16; ++r) p1[r] = __builtin_amdgcn_exp2f(p1[r]);
;   float ps = 0; for (int r = 0; r < 16; ++r) ps += p0[r]; for (int r = 0; r < 16; ++r) ps += p1[r];
;   { auto rr = __builtin_amdgcn_permlane32_swap(__float_as_uint(ps), __float_as_uint(ps), false, false);
;     ps = __uint_as_float(rr[0]) + __uint_as_float(rr[1]); }
;   l_reg = l_reg * alpha + ps;
;     ...
;   PK4(p0, 0, pa0); PK4(p0, 8, pa1); PK4(p1, 0, pa2); PK4(p1, 8, pa3);
;     ...
; }
; __device__ __forceinline__ void kload(bf16x8 (&kf)[8], const char* Ks, int r32, int hi, int sb) {
; #pragma unroll
;   for (int d0 = 0; d0 < 4; ++d0) { const int cb = sb + (d0 * 16 + hi * 8) * 2;
;     kf[2 * d0] = *reinterpret_cast<const bf16x8*>(Ks + KSWZ(r32, cb)); kf[2 * d0 + 1] = *reinterpret_cast<const bf16x8*>(Ks + KSWZ(32 + r32, cb)); }
; }
; __device__ __forceinline__ void kmma(f32x16& p0, f32x16& p1, const bf16x8 (&kf)[8], const bf16x8* qr) {
;   asm volatile("s_waitcnt lgkmcnt(0)" ::: "memory"); SBAR();
;   p0 = f32x16{}; p1 = f32x16{};
; #pragma unroll
;   for (int d0 = 0; d0 < 4; ++d0) { p0 = __builtin_amdgcn_mfma_f32_32x32x16_bf16(kf[2 * d0], qr[d0], p0, 0, 0, 0); p1 = __builtin_amdgcn_mfma_f32_32x32x16_bf16(kf[2 * d0 + 1], qr[d0], p1, 0, 0, 0); }
; }
; __device__ __forceinline__ void qkt(f32x16& p0, f32x16& p1, const char* Ks, const bf16x8* qr, int r32, int hi, int sb) {
;   bf16x8 kf[8]; kload(kf, Ks, r32, hi, sb); SBAR(); kmma(p0, p1, kf, qr);
; }
.LBB0_774:
	s_waitcnt vmcnt(4)
	s_barrier
	s_and_b32 s46, s13, 0xc000
	v_add_u32_e32 v244, s46, v164
	s_add_i32 s0, s12, 1
	s_mul_i32 s1, s0, 0xab
	s_bfe_u32 s1, s1, 0x70009
	s_mul_i32 s1, s1, 3
	s_sub_i32 s0, s0, s1
	s_and_b32 s0, s0, 0xff
	s_lshl_b32 s0, s0, 14
	s_add_i32 s0, s0, 0
	v_add_u32_e32 v70, s0, v169
	v_add_u32_e32 v74, s0, v170
	ds_read_b128 v[66:69], v70
	ds_read_b128 v[70:73], v70 offset:8192
	ds_read_b128 v[98:101], v74
	ds_read_b128 v[102:105], v74 offset:8192
	v_add_u32_e32 v74, s0, v171
	ds_read_b128 v[106:109], v74
	ds_read_b128 v[110:113], v74 offset:8192
	v_add_u32_e32 v74, s0, v172
	ds_read_b128 v[134:137], v74
	ds_read_b128 v[174:177], v74 offset:8192
	ds_read_b64_tr_b16 v[228:229], v244 offset:0
	ds_read_b64_tr_b16 v[230:231], v244 offset:0x800
	ds_read_b64_tr_b16 v[232:233], v244 offset:0x1000
	ds_read_b64_tr_b16 v[234:235], v244 offset:0x1800
	ds_read_b64_tr_b16 v[236:237], v244 offset:0x2000
	ds_read_b64_tr_b16 v[238:239], v244 offset:0x2800
	ds_read_b64_tr_b16 v[240:241], v244 offset:0x3000
	ds_read_b64_tr_b16 v[242:243], v244 offset:0x3800
	v_exp_f32_e32 v210, v82
	v_exp_f32_e32 v211, v83
	v_exp_f32_e32 v212, v84
	v_exp_f32_e32 v213, v85
	v_exp_f32_e32 v214, v86
	v_exp_f32_e32 v215, v87
	v_add_f32_e32 v216, 0, v192
	v_add_f32_e32 v216, v193, v216
	v_add_f32_e32 v216, v194, v216
	v_add_f32_e32 v216, v195, v216
	v_exp_f32_e32 v149, v149
	v_exp_f32_e32 v150, v150
	v_exp_f32_e32 v151, v151
	v_exp_f32_e32 v186, v186
	v_exp_f32_e32 v187, v187
	v_exp_f32_e32 v188, v188
	s_waitcnt lgkmcnt(15)
	v_mfma_f32_32x32x16_bf16 v[82:97], v[66:69], v[126:129], 0
	v_exp_f32_e32 v189, v189
	s_add_i32 s46, s12, 3
	v_exp_f32_e32 v208, v208
	s_cmpk_lt_u32 s12, 0x7d
	v_exp_f32_e32 v209, v209
	s_cselect_b64 s[42:43], -1, 0
	v_exp_f32_e32 v148, v148
	v_add_f32_e32 v248, v196, v216
	v_add_f32_e32 v248, v197, v248
	v_add_f32_e32 v248, v198, v248
	s_waitcnt lgkmcnt(14)
	v_mfma_f32_32x32x16_bf16 v[66:81], v[70:73], v[126:129], 0
	v_add_f32_e32 v248, v199, v248
	s_and_b64 s[44:45], s[42:43], exec
	v_add_f32_e32 v248, v200, v248
	s_cselect_b32 s44, 0, 0xffffff80
	v_add_f32_e32 v248, v201, v248
	s_add_i32 s58, s46, s44
	v_add_f32_e32 v248, v202, v248
	v_add_f32_e32 v248, v203, v248
	v_add_f32_e32 v248, v204, v248
	v_add_f32_e32 v248, v205, v248
	s_waitcnt lgkmcnt(13)
	v_mfma_f32_32x32x16_bf16 v[82:97], v[98:101], v[122:125], v[82:97]
	v_add_f32_e32 v248, v206, v248
	s_and_b64 s[42:43], s[42:43], exec
	v_add_f32_e32 v248, v207, v248
	s_cselect_b32 s43, s9, s30
	v_add_f32_e32 v248, v210, v248
	s_cselect_b32 s42, s8, s26
	v_add_f32_e32 v248, v211, v248
	v_add_f32_e32 v248, v212, v248
	v_add_f32_e32 v248, v213, v248
	v_add_f32_e32 v248, v214, v248
	s_waitcnt lgkmcnt(12)
	v_mfma_f32_32x32x16_bf16 v[66:81], v[102:105], v[122:125], v[66:81]
	v_add_f32_e32 v248, v215, v248
	s_lshl_b64 s[44:45], s[58:59], 17
	v_add_f32_e32 v248, v149, v248
	s_lshl_b64 s[42:43], s[42:43], 11
	v_add_f32_e32 v248, v150, v248
	s_add_u32 s44, s44, s42
	v_add_f32_e32 v248, v151, v248
	s_addc_u32 s45, s45, s43
	v_add_f32_e32 v248, v186, v248
	v_add_f32_e32 v248, v187, v248
	v_add_f32_e32 v248, v188, v248
	v_add_f32_e32 v248, v189, v248
	s_waitcnt lgkmcnt(11)
	v_mfma_f32_32x32x16_bf16 v[82:97], v[106:109], v[118:121], v[82:97]
	v_add_f32_e32 v248, v208, v248
	s_add_u32 s42, s20, s44
	v_add_f32_e32 v248, v209, v248
	s_addc_u32 s43, s21, s45
	v_add_f32_e32 v99, v148, v248
	s_add_u32 s44, s22, s44
	v_mov_b32_e32 v100, v99
	s_nop 1
	v_permlane32_swap_b32_e32 v99, v100
	v_cvt_pk_bf16_f32 v102, v192, v193
	v_cvt_pk_bf16_f32 v103, v194, v195
	s_waitcnt lgkmcnt(10)
	v_mfma_f32_32x32x16_bf16 v[66:81], v[110:113], v[118:121], v[66:81]
	v_cvt_pk_bf16_f32 v104, v196, v197
	s_mul_i32 s47, s46, 0xab
	v_cvt_pk_bf16_f32 v105, v198, v199
	s_addc_u32 s45, s23, s45
	v_cvt_pk_bf16_f32 v106, v200, v201
	s_bfe_u32 s47, s47, 0x70009
	v_cvt_pk_bf16_f32 v107, v202, v203
	v_cvt_pk_bf16_f32 v108, v204, v205
	v_cvt_pk_bf16_f32 v109, v206, v207
	v_cvt_pk_bf16_f32 v110, v210, v211
	s_waitcnt lgkmcnt(9)
	v_mfma_f32_32x32x16_bf16 v[82:97], v[134:137], v[114:117], v[82:97]
	v_cvt_pk_bf16_f32 v111, v212, v213
	s_mul_i32 s47, s47, 3
	v_cvt_pk_bf16_f32 v112, v214, v215
	s_sub_i32 s46, s46, s47
	v_cvt_pk_bf16_f32 v113, v149, v150
	s_and_b32 s46, s46, 0xff
	v_cvt_pk_bf16_f32 v134, v151, v186
	v_cvt_pk_bf16_f32 v135, v187, v188
	v_cvt_pk_bf16_f32 v136, v189, v208
	v_cvt_pk_bf16_f32 v137, v209, v148
	s_waitcnt lgkmcnt(8)
	v_mfma_f32_32x32x16_bf16 v[66:81], v[174:177], v[114:117], v[66:81]
	v_permlane32_swap_b32_e32 v102, v104
	s_lshl_b32 s46, s46, 14
	v_permlane32_swap_b32_e32 v103, v105
	s_add_i32 s46, s46, s27
	v_permlane32_swap_b32_e32 v106, v108
	s_and_b32 s47, s36, 0xc000
	v_permlane32_swap_b32_e32 v107, v109
	s_add_i32 s47, s47, s31
	v_permlane32_swap_b32_e32 v110, v112
	v_permlane32_swap_b32_e32 v111, v113
	v_permlane32_swap_b32_e32 v134, v136
	v_permlane32_swap_b32_e32 v135, v137
	s_cmpk_gt_u32 s12, 0x80
	s_cselect_b64 s[10:11], -1, 0
	s_and_b64 vcc, exec, s[10:11]
	s_cbranch_vccnz .LBB0_776
	v_lshl_add_u64 v[246:247], s[42:43], 0, v[146:147]
	s_mov_b32 m0, s46
	s_nop 0
	global_load_lds_dwordx4 v[246:247], off
	v_lshl_add_u64 v[246:247], s[44:45], 0, v[142:143]
	s_mov_b32 m0, s47
	s_nop 0
	global_load_lds_dwordx4 v[246:247], off
	v_lshl_add_u64 v[246:247], s[42:43], 0, v[144:145]
	s_add_i32 m0, s46, 0x2000
	s_nop 0
	global_load_lds_dwordx4 v[246:247], off
	v_lshl_add_u64 v[246:247], s[44:45], 0, v[154:155]
	s_add_i32 m0, s47, 0x2000
	s_nop 0
	global_load_lds_dwordx4 v[246:247], off
; __device__ __forceinline__ void partialSM(f32x16& p0, f32x16& p1, float& m_reg, float& mn, float& alpha) {
;   constexpr float C = SCALE * 1.4426950408889634f;
;   float pmax = p0[0]; for (int r = 1; r < 16; ++r) pmax = fmaxf(pmax, p0[r]); for (int r = 0; r < 16; ++r) pmax = fmaxf(pmax, p1[r]);
;   { auto rr = __builtin_amdgcn_permlane32_swap(__float_as_uint(pmax), __float_as_uint(pmax), false, false);
;     pmax = fmaxf(__uint_as_float(rr[0]), __uint_as_float(rr[1])); }
;   if (__builtin_expect(__all(pmax - m_reg <= THR / SCALE), 1)) { mn = m_reg; alpha = 1.f; }
;   else { mn = fmaxf(m_reg, pmax); alpha = __builtin_amdgcn_exp2f((m_reg - mn) * C); m_reg = mn; }
;   float mnC = -mn * C;
;   for (int r = 0; r < 16; ++r) p0[r] = fmaf(p0[r], C, mnC); for (int r = 0; r < 16; ++r) p1[r] = fmaf(p1[r], C, mnC);
;   for (int r = 0; r < 16; ++r) p0[r] = __builtin_amdgcn_exp2f(p0[r]);
; }
; template <int D0> __device__ __forceinline__ void v_frag_read(VFrag& f, int vb) {
;   f.l0 = tr_read<v_rd_off(D0, 0, 0)>(vb); f.h0 = tr_read<v_rd_off(D0, 0, 1)>(vb); f.l1 = tr_read<v_rd_off(D0, 1, 0)>(vb); f.h1 = tr_read<v_rd_off(D0, 1, 1)>(vb);
;   f.l2 = tr_read<v_rd_off(D0, 2, 0)>(vb); f.h2 = tr_read<v_rd_off(D0, 2, 1)>(vb); f.l3 = tr_read<v_rd_off(D0, 3, 0)>(vb); f.h3 = tr_read<v_rd_off(D0, 3, 1)>(vb);
; }
; __device__ __forceinline__ void pv_mma(f32x16& od, const VFrag& f, bf16x8 pa0, bf16x8 pa1, bf16x8 pa2, bf16x8 pa3) {
;     ...
;   od = __builtin_amdgcn_mfma_f32_32x32x16_bf16(pa0, PK(f.l0, f.h0), od, 0, 0, 0);
;   od = __builtin_amdgcn_mfma_f32_32x32x16_bf16(pa1, PK(f.l1, f.h1), od, 0, 0, 0);
;   od = __builtin_amdgcn_mfma_f32_32x32x16_bf16(pa2, PK(f.l2, f.h2), od, 0, 0, 0);
;   od = __builtin_amdgcn_mfma_f32_32x32x16_bf16(pa3, PK(f.l3, f.h3), od, 0, 0, 0);
;     ...
; }
; __device__ __forceinline__ void pv_d0(f32x16* o, int vb, bf16x8 pa0, bf16x8 pa1, bf16x8 pa2, bf16x8 pa3) {
;   VFrag fa, fb;
;   v_frag_read<0>(fa, vb);
;   asm volatile("s_waitcnt lgkmcnt(0)" ::: "memory"); SBAR();
;   v_frag_read<1>(fb, vb); SBAR();
;   pv_mma(o[0], fa, pa0, pa1, pa2, pa3); SBAR();
;   asm volatile("s_waitcnt lgkmcnt(0)" ::: "memory"); SBAR();
;   v_frag_read<2>(fa, vb); SBAR();
;   pv_mma(o[1], fb, pa0, pa1, pa2, pa3); SBAR();
;   asm volatile("s_waitcnt lgkmcnt(0)" ::: "memory"); SBAR();
;   v_frag_read<3>(fb, vb); SBAR();
;   pv_mma(o[2], fa, pa0, pa1, pa2, pa3); SBAR();
.LBB0_776:
	ds_read_b64_tr_b16 v[204:205], v244 offset:0x200
	ds_read_b64_tr_b16 v[206:207], v244 offset:0xa00
	ds_read_b64_tr_b16 v[208:209], v244 offset:0x1200
	ds_read_b64_tr_b16 v[210:211], v244 offset:0x1a00
	ds_read_b64_tr_b16 v[212:213], v244 offset:0x2200
	ds_read_b64_tr_b16 v[214:215], v244 offset:0x2a00
	ds_read_b64_tr_b16 v[216:217], v244 offset:0x3200
	ds_read_b64_tr_b16 v[218:219], v244 offset:0x3a00
	s_waitcnt lgkmcnt(14)
	v_mfma_f32_32x32x16_bf16 v[18:33], v[102:105], v[228:231], v[18:33]
	v_max_f32_e32 v245, v83, v83
	v_max_f32_e32 v246, v82, v82
	v_max_f32_e32 v245, v246, v245
	v_max3_f32 v245, v245, v84, v85
	v_max3_f32 v245, v245, v86, v87
	v_max3_f32 v245, v245, v88, v89
	v_max3_f32 v245, v245, v90, v91
	v_max3_f32 v245, v245, v92, v93
	s_waitcnt lgkmcnt(12)
	v_mfma_f32_32x32x16_bf16 v[18:33], v[106:109], v[232:235], v[18:33]
	v_max3_f32 v245, v245, v94, v95
	v_max3_f32 v245, v245, v96, v97
	v_max3_f32 v245, v245, v66, v67
	v_max3_f32 v245, v245, v68, v69
	v_max3_f32 v245, v245, v70, v71
	v_max3_f32 v245, v245, v72, v73
	v_max3_f32 v245, v245, v74, v75
	v_max3_f32 v245, v245, v76, v77
	s_waitcnt lgkmcnt(10)
	v_mfma_f32_32x32x16_bf16 v[18:33], v[110:113], v[236:239], v[18:33]
	v_max3_f32 v245, v245, v78, v79
	v_max3_f32 v245, v245, v80, v81
	v_mov_b32_e32 v246, v245
	s_nop 1
	v_permlane32_swap_b32_e32 v245, v246
	v_max_f32_e32 v246, v246, v246
	v_max_f32_e32 v245, v245, v245
	v_max_f32_e32 v245, v245, v246
	v_sub_f32_e32 v246, v245, v133
	s_waitcnt lgkmcnt(8)
	v_mfma_f32_32x32x16_bf16 v[18:33], v[134:137], v[240:243], v[18:33]
	v_cmp_ge_f32_e32 vcc, s63, v246
	v_max_f32_e32 v246, v133, v133
	v_max_f32_e32 v245, v246, v245
	v_sub_f32_e32 v246, v133, v245
	v_mul_f32_e32 v246, 0x3e38aa3b, v246
	v_exp_f32_e32 v246, v246
	s_cmp_eq_u64 vcc, exec
	s_cselect_b64 s[0:1], -1, 0
	v_cndmask_b32_e64 v247, v246, 1.0, s[0:1]
	ds_read_b64_tr_b16 v[228:229], v244 offset:0x400
	ds_read_b64_tr_b16 v[230:231], v244 offset:0xc00
	ds_read_b64_tr_b16 v[232:233], v244 offset:0x1400
	ds_read_b64_tr_b16 v[234:235], v244 offset:0x1c00
	ds_read_b64_tr_b16 v[236:237], v244 offset:0x2400
	ds_read_b64_tr_b16 v[238:239], v244 offset:0x2c00
	ds_read_b64_tr_b16 v[240:241], v244 offset:0x3400
	ds_read_b64_tr_b16 v[242:243], v244 offset:0x3c00
	v_cndmask_b32_e64 v174, v245, v133, s[0:1]
	v_mul_f32_e32 v98, 0xbe38aa3b, v174
	s_waitcnt lgkmcnt(14)
	v_mfma_f32_32x32x16_bf16 v[50:65], v[102:105], v[204:207], v[50:65]
	v_fmamk_f32 v82, v82, 0x3e38aa3b, v98
	v_fmamk_f32 v83, v83, 0x3e38aa3b, v98
	v_fmamk_f32 v84, v84, 0x3e38aa3b, v98
	v_fmamk_f32 v85, v85, 0x3e38aa3b, v98
	s_waitcnt lgkmcnt(12)
	v_mfma_f32_32x32x16_bf16 v[50:65], v[106:109], v[208:211], v[50:65]
	v_fmamk_f32 v86, v86, 0x3e38aa3b, v98
	v_fmamk_f32 v87, v87, 0x3e38aa3b, v98
	v_fmamk_f32 v88, v88, 0x3e38aa3b, v98
	v_fmamk_f32 v89, v89, 0x3e38aa3b, v98
	s_waitcnt lgkmcnt(10)
	v_mfma_f32_32x32x16_bf16 v[50:65], v[110:113], v[212:215], v[50:65]
	v_fmamk_f32 v90, v90, 0x3e38aa3b, v98
	v_fmamk_f32 v91, v91, 0x3e38aa3b, v98
	v_fmamk_f32 v92, v92, 0x3e38aa3b, v98
	v_fmamk_f32 v93, v93, 0x3e38aa3b, v98
	s_waitcnt lgkmcnt(8)
	v_mfma_f32_32x32x16_bf16 v[50:65], v[134:137], v[216:219], v[50:65]
	v_fmamk_f32 v94, v94, 0x3e38aa3b, v98
	v_fmamk_f32 v95, v95, 0x3e38aa3b, v98
	v_fmamk_f32 v96, v96, 0x3e38aa3b, v98
	v_fmamk_f32 v97, v97, 0x3e38aa3b, v98
	ds_read_b64_tr_b16 v[204:205], v244 offset:0x600
	ds_read_b64_tr_b16 v[206:207], v244 offset:0xe00
	ds_read_b64_tr_b16 v[208:209], v244 offset:0x1600
	ds_read_b64_tr_b16 v[210:211], v244 offset:0x1e00
	ds_read_b64_tr_b16 v[212:213], v244 offset:0x2600
	ds_read_b64_tr_b16 v[214:215], v244 offset:0x2e00
	ds_read_b64_tr_b16 v[216:217], v244 offset:0x3600
	ds_read_b64_tr_b16 v[218:219], v244 offset:0x3e00
	s_waitcnt lgkmcnt(14)
	v_mfma_f32_32x32x16_bf16 v[34:49], v[102:105], v[228:231], v[34:49]
	s_mov_b32 s46, 0x3e38aa3b
	v_pk_fma_f32 v[80:81], v[80:81], s[46:47], v[98:99] op_sel_hi:[1,0,0]
	v_pk_fma_f32 v[78:79], v[78:79], s[46:47], v[98:99] op_sel_hi:[1,0,0]
	s_waitcnt lgkmcnt(12)
	v_mfma_f32_32x32x16_bf16 v[34:49], v[106:109], v[232:235], v[34:49]
	v_pk_fma_f32 v[76:77], v[76:77], s[46:47], v[98:99] op_sel_hi:[1,0,0]
	v_pk_fma_f32 v[74:75], v[74:75], s[46:47], v[98:99] op_sel_hi:[1,0,0]
	v_pk_fma_f32 v[72:73], v[72:73], s[46:47], v[98:99] op_sel_hi:[1,0,0]
	s_waitcnt lgkmcnt(10)
	v_mfma_f32_32x32x16_bf16 v[34:49], v[110:113], v[236:239], v[34:49]
	v_pk_fma_f32 v[70:71], v[70:71], s[46:47], v[98:99] op_sel_hi:[1,0,0]
	v_pk_fma_f32 v[68:69], v[68:69], s[46:47], v[98:99] op_sel_hi:[1,0,0]
	v_pk_fma_f32 v[66:67], v[66:67], s[46:47], v[98:99] op_sel_hi:[1,0,0]
	s_waitcnt lgkmcnt(8)
	v_mfma_f32_32x32x16_bf16 v[34:49], v[134:137], v[240:243], v[34:49]
	v_exp_f32_e32 v175, v82
	v_exp_f32_e32 v177, v83
	v_exp_f32_e32 v192, v84
	s_waitcnt lgkmcnt(6)
	v_mfma_f32_32x32x16_bf16 v[2:17], v[102:105], v[204:207], v[2:17]
	v_mov_b32_e32 v205, v247
	v_exp_f32_e32 v204, v97
	v_exp_f32_e32 v195, v85
	v_exp_f32_e32 v196, v86
	v_exp_f32_e32 v199, v87
	v_exp_f32_e32 v200, v88
	s_waitcnt lgkmcnt(4)
	v_mfma_f32_32x32x16_bf16 v[2:17], v[106:109], v[208:211], v[2:17]
	v_exp_f32_e32 v203, v89
	v_exp_f32_e32 v176, v90
	v_exp_f32_e32 v193, v91
	v_exp_f32_e32 v194, v92
	s_waitcnt lgkmcnt(2)
	v_mfma_f32_32x32x16_bf16 v[2:17], v[110:113], v[212:215], v[2:17]
	v_exp_f32_e32 v197, v93
	v_exp_f32_e32 v198, v94
	v_exp_f32_e32 v201, v95
	v_exp_f32_e32 v202, v96
	s_waitcnt lgkmcnt(0)
	v_mfma_f32_32x32x16_bf16 v[2:17], v[134:137], v[216:219], v[2:17]
	v_cmp_gt_f32_e32 vcc, 1.0, v205
	s_cbranch_vccz .LBB0_780
	s_and_saveexec_b64 s[12:13], s[40:41]
	ds_write_b32 v162, v205 offset:128
	s_or_b64 exec, exec, s[12:13]
	s_waitcnt lgkmcnt(0)
	v_add_u32_e32 v101, s18, v140
	ds_read_b128 v[102:105], v101 offset:224
	ds_read_b128 v[106:109], v101 offset:192
	ds_read_b128 v[110:113], v101 offset:160
	ds_read_b128 v[134:137], v101 offset:128
	s_waitcnt lgkmcnt(0)
	v_pk_mul_f32 v[30:31], v[30:31], v[102:103]
	v_pk_mul_f32 v[26:27], v[26:27], v[106:107]
	v_pk_mul_f32 v[22:23], v[22:23], v[110:111]
	v_pk_mul_f32 v[32:33], v[32:33], v[104:105]
	v_pk_mul_f32 v[28:29], v[28:29], v[108:109]
	v_pk_mul_f32 v[24:25], v[24:25], v[112:113]
	v_pk_mul_f32 v[20:21], v[20:21], v[136:137]
	v_pk_mul_f32 v[18:19], v[18:19], v[134:135]
	v_pk_mul_f32 v[62:63], v[62:63], v[102:103]
	v_pk_mul_f32 v[58:59], v[58:59], v[106:107]
	v_pk_mul_f32 v[54:55], v[54:55], v[110:111]
	v_pk_mul_f32 v[64:65], v[64:65], v[104:105]
	v_pk_mul_f32 v[60:61], v[60:61], v[108:109]
	v_pk_mul_f32 v[56:57], v[56:57], v[112:113]
	v_pk_mul_f32 v[52:53], v[52:53], v[136:137]
	v_pk_mul_f32 v[50:51], v[50:51], v[134:135]
	v_pk_mul_f32 v[46:47], v[46:47], v[102:103]
	v_pk_mul_f32 v[42:43], v[42:43], v[106:107]
	v_pk_mul_f32 v[38:39], v[38:39], v[110:111]
	v_pk_mul_f32 v[48:49], v[48:49], v[104:105]
	v_pk_mul_f32 v[44:45], v[44:45], v[108:109]
	v_pk_mul_f32 v[40:41], v[40:41], v[112:113]
	v_pk_mul_f32 v[36:37], v[36:37], v[136:137]
	v_pk_mul_f32 v[34:35], v[34:35], v[134:135]
	v_pk_mul_f32 v[14:15], v[14:15], v[102:103]
	v_pk_mul_f32 v[10:11], v[10:11], v[106:107]
	v_pk_mul_f32 v[6:7], v[6:7], v[110:111]
	v_pk_mul_f32 v[16:17], v[16:17], v[104:105]
	v_pk_mul_f32 v[12:13], v[12:13], v[108:109]
	v_pk_mul_f32 v[8:9], v[8:9], v[112:113]
	v_pk_mul_f32 v[4:5], v[4:5], v[136:137]
	v_pk_mul_f32 v[2:3], v[2:3], v[134:135]
